# E51: E50 plus next layer's Win/Wo weight conversion done by the idle work-groups of MLP-up's last round; PREP converts Win/Wo only for layer 0
# baseline (speedup 1.0000x reference)
; #define P (*get_params())
; __global__ void __launch_bounds__(512) fwd_megakernel(Params Parg) {
;     ...
;       } else {
;         conv_matrix(P.c_w_in + (size_t)j * 1024 * 3072, 1024, 3072, 3072, Win, nullptr, tile);
;       }
.LBB0_99:
	s_bitcmp1_b32 s44, 0
	s_cselect_b64 s[12:13], -1, 0
	s_lshr_b32 s34, s44, 1
	s_and_b64 vcc, exec, s[12:13]
	s_mov_b64 s[4:5], -1
	s_cbranch_vccz .LBB0_152
	s_waitcnt lgkmcnt(0)
	v_readlane_b32 s8, v254, 0
	v_readlane_b32 s9, v254, 1
	s_mov_b64 s[6:7], s[0:1]
	s_mov_b64 s[4:5], s[0:1]
	v_mov_b32_e32 v0, v187
	s_andn2_b64 vcc, exec, s[8:9]
	s_cmp_lg_u32 s44, 0
	s_cbranch_scc1 .LBB0_151
	s_cbranch_vccnz .LBB0_151
	s_load_dwordx2 s[6:7], s[6:7], 0x98
	s_mul_i32 s8, s34, 0x300000
	s_load_dwordx2 s[4:5], s[4:5], 0xd8
	s_mov_b32 s9, s35
	s_lshl_b64 s[8:9], s[8:9], 2
	v_and_b32_e32 v9, 63, v0
	v_ashrrev_i32_e32 v12, 6, v0
	v_ashrrev_i32_e32 v13, 3, v0
	v_lshlrev_b32_e32 v0, 3, v0
	s_waitcnt lgkmcnt(0)
	s_add_u32 s6, s6, s8
	v_and_b32_e32 v8, 56, v0
	v_lshlrev_b32_e32 v0, 2, v9
	v_mul_lo_u32 v2, v12, s94
	s_addc_u32 s7, s7, s9
	v_lshl_add_u32 v1, v13, 2, 16
	v_add3_u32 v14, 16, v0, v2
	v_add3_u32 v15, 16, v2, v0
	v_mul_u32_u24_e32 v0, 0x104, v8
	v_mov_b32_e32 v142, v144
	v_mov_b32_e32 v143, v144
	s_add_u32 s8, s4, 0x8200000
	v_mad_u32_u24 v16, v8, s94, v1
	v_mov_b32_e32 v145, v144
	v_mov_b32_e32 v146, v144
	v_mov_b32_e32 v147, v144
	v_mov_b32_e32 v148, v144
	v_mov_b32_e32 v149, v144
	v_add_u32_e32 v17, v1, v0
	v_mov_b64_e32 v[0:1], v[142:143]
	s_addc_u32 s9, s5, 0
	s_lshl_b32 s20, s71, 6
	v_readlane_b32 s21, v255, 8
	s_mov_b32 s22, s2
	v_mov_b64_e32 v[2:3], v[144:145]
	v_mov_b64_e32 v[4:5], v[146:147]
	v_mov_b64_e32 v[6:7], v[148:149]
	s_branch .LBB0_103

; #define P (*get_params())
; __global__ void __launch_bounds__(512) fwd_megakernel(Params Parg) {
;     ...
;       if (even) {
;         conv_matrix(P.a_w_in + (size_t)j * 1024 * 3264, 1024, 3264, 3328, Win, nullptr, tile);
;         conv_matrix(P.mla_w_uq + (size_t)j * 384 * 768, 384, 768, 768, Wuq, P.mla_q_norm + j * 384, tile);
;         conv_matrix(P.mla_w_ukv + (size_t)j * 256 * 1024, 256, 1024, 1024, Wukv, P.mla_kv_norm + j * 256, tile);
.LBB0_152:
	s_andn2_b64 vcc, exec, s[4:5]
	s_cbranch_vccnz .LBB0_368
	s_waitcnt lgkmcnt(0)
	v_readlane_b32 s8, v254, 2
	v_readlane_b32 s9, v254, 3
	s_mov_b64 s[6:7], s[0:1]
	s_mov_b64 s[4:5], s[0:1]
	v_mov_b32_e32 v0, v187
	s_andn2_b64 vcc, exec, s[8:9]
	s_cmp_lg_u32 s44, 0
	s_cbranch_scc1 .LBB0_204
	s_cbranch_vccnz .LBB0_204
	s_load_dwordx2 s[6:7], s[6:7], 0x50
	s_mul_i32 s9, s34, 0xcc0000
	s_load_dwordx2 s[4:5], s[4:5], 0xd8
	v_and_b32_e32 v9, 63, v0
	v_ashrrev_i32_e32 v12, 6, v0
	v_ashrrev_i32_e32 v13, 3, v0
	v_lshlrev_b32_e32 v0, 3, v0
	s_mul_hi_u32 s8, s34, 0xcc0000
	s_waitcnt lgkmcnt(0)
	s_add_u32 s6, s6, s9
	v_and_b32_e32 v8, 56, v0
	v_lshlrev_b32_e32 v0, 2, v9
	v_mul_lo_u32 v2, v12, s94
	s_addc_u32 s7, s7, s8
	v_lshl_add_u32 v1, v13, 2, 16
	v_add3_u32 v14, 16, v0, v2
	v_add3_u32 v15, 16, v2, v0
	v_mul_u32_u24_e32 v0, 0x104, v8
	v_mov_b32_e32 v142, v144
	v_mov_b32_e32 v143, v144
	s_add_u32 s8, s4, 0x8200000
	v_mad_u32_u24 v16, v8, s94, v1
	v_mov_b32_e32 v145, v144
	v_mov_b32_e32 v146, v144
	v_mov_b32_e32 v147, v144
	v_mov_b32_e32 v148, v144
	v_mov_b32_e32 v149, v144
	v_add_u32_e32 v17, v1, v0
	v_mov_b64_e32 v[0:1], v[142:143]
	s_addc_u32 s9, s5, 0
	s_lshl_b32 s20, s71, 6
	v_readlane_b32 s21, v255, 8
	s_mov_b32 s22, s2
	v_mov_b64_e32 v[2:3], v[144:145]
	v_mov_b64_e32 v[4:5], v[146:147]
	v_mov_b64_e32 v[6:7], v[148:149]
	s_branch .LBB0_156

; #define P (*get_params())
; __global__ void __launch_bounds__(512) fwd_megakernel(Params Parg) {
;     ...
;       conv_matrix(P.w_o + (size_t)l * 1024 * 1024, 1024, 1024, 1024, Wo, nullptr, tile);
.LBB0_368:
	s_waitcnt lgkmcnt(0)
	v_readlane_b32 s8, v254, 8
	v_readlane_b32 s9, v254, 9
	s_mov_b32 s45, s35
	s_mov_b64 s[6:7], s[0:1]
	v_cndmask_b32_e64 v1, 0, 1, s[8:9]
	v_cmp_ne_u32_e64 s[10:11], 1, v1
	s_mov_b64 s[4:5], s[0:1]
	v_mov_b32_e32 v0, v187
	v_writelane_b32 v255, s10, 26
	s_andn2_b64 vcc, exec, s[8:9]
	s_nop 0
	v_writelane_b32 v255, s11, 27
	s_cmp_lg_u32 s44, 0
	s_cbranch_scc1 .LBB0_419
	s_cbranch_vccnz .LBB0_419
	s_load_dwordx2 s[6:7], s[6:7], 0x38
	s_lshl_b64 s[8:9], s[44:45], 22
	s_load_dwordx2 s[10:11], s[4:5], 0xd8
	v_and_b32_e32 v9, 63, v0
	v_ashrrev_i32_e32 v14, 6, v0
	v_ashrrev_i32_e32 v15, 3, v0
	v_lshlrev_b32_e32 v0, 3, v0
	s_waitcnt lgkmcnt(0)
	s_add_u32 s4, s6, s8
	v_and_b32_e32 v8, 56, v0
	v_lshlrev_b32_e32 v0, 2, v9
	v_mul_lo_u32 v2, v14, s94
	s_addc_u32 s5, s7, s9
	v_lshl_add_u32 v1, v15, 2, 16
	v_add3_u32 v16, 16, v0, v2
	v_add3_u32 v17, 16, v2, v0
	v_mul_u32_u24_e32 v0, 0x104, v8
	v_mov_b32_e32 v142, v144
	v_mov_b32_e32 v143, v144
	s_add_u32 s10, s10, 0x8880000
	v_mad_u32_u24 v18, v8, s94, v1
	v_mov_b32_e32 v145, v144
	v_mov_b32_e32 v146, v144
	v_mov_b32_e32 v147, v144
	v_mov_b32_e32 v148, v144
	v_mov_b32_e32 v149, v144
	v_add_u32_e32 v19, v1, v0
	v_mov_b64_e32 v[0:1], v[142:143]
	s_addc_u32 s11, s11, 0
	s_lshl_b32 s20, s71, 6
	v_readlane_b32 s21, v255, 8
	s_mov_b32 s22, s2
	v_mov_b64_e32 v[2:3], v[144:145]
	v_mov_b64_e32 v[4:5], v[146:147]
	v_mov_b64_e32 v[6:7], v[148:149]
	s_branch .LBB0_371

; __device__ __forceinline__ int tid_() { int t = threadIdx.x; asm volatile("" : "+v"(t)); return t; }
; #define P (*get_params())
; __device__ __forceinline__ void conv_matrix(const float* __restrict__ src, int K, int N, int Npad, bf16_t* __restrict__ dst, const float* __restrict__ scale, float* tile) {
;   const int nk = K / 64, nn = Npad / 64, tot = nk * nn;
;   const int tid = tid_(), tx = tid & 63, ty = tid >> 6, nl = tid >> 3, ks = (tid & 7) * 8;
;   for (int i0 = blockIdx.x; i0 < tot; i0 += 2 * gridDim.x) {
;     const int i1 = i0 + gridDim.x; const bool has1 = i1 < tot;
;     const int k0a = (i0 % nk) * 64, n0a = (i0 / nk) * 64, k0b = has1 ? (i1 % nk) * 64 : 0, n0b = has1 ? (i1 / nk) * 64 : 0;
;     float va[8], vb[8];
; #pragma unroll
;     for (int i = 0; i < 8; ++i) { const int k = k0a + ty + 8 * i, n = n0a + tx; float v = (n < N) ? src[(size_t)k * N + n] : 0.f; if (scale) v *= scale[k]; va[i] = v; }
;     if (has1) {
; #pragma unroll
;       for (int i = 0; i < 8; ++i) { const int k = k0b + ty + 8 * i, n = n0b + tx; float v = (n < N) ? src[(size_t)k * N + n] : 0.f; if (scale) v *= scale[k]; vb[i] = v; }
;     }
; __global__ void __launch_bounds__(512) fwd_megakernel(Params Parg) {
;     ...
;         conv_matrix(P.a_w_in + (size_t)j * 1024 * 3264, 1024, 3264, 3328, Win, nullptr, tile);
;         conv_matrix(P.mla_w_uq + (size_t)j * 384 * 768, 384, 768, 768, Wuq, P.mla_q_norm + j * 384, tile);
;         conv_matrix(P.mla_w_ukv + (size_t)j * 256 * 1024, 256, 1024, 1024, Wukv, P.mla_kv_norm + j * 256, tile);
;       } else {
;         conv_matrix(P.c_w_in + (size_t)j * 1024 * 3072, 1024, 3072, 3072, Win, nullptr, tile);
;       }
;       conv_matrix(P.w_o + (size_t)l * 1024 * 1024, 1024, 1024, 1024, Wo, nullptr, tile);
.LBB0_2778:
	s_cmp_lt_u32 s2, 16
	s_cbranch_scc1 .Lcvm_skip
	v_readlane_b32 s8, v255, 32
	s_cmp_gt_u32 s8, 2
	s_cbranch_scc1 .Lcvm_skip
	v_writelane_b32 v255, s4, 46
	v_writelane_b32 v255, s5, 47
	v_writelane_b32 v255, s6, 48
	v_writelane_b32 v255, s7, 49
	v_writelane_b32 v255, s10, 50
	v_writelane_b32 v255, s11, 51
	v_writelane_b32 v255, s12, 52
	v_writelane_b32 v255, s13, 53
	v_writelane_b32 v255, s14, 54
	v_writelane_b32 v255, s15, 55
	v_writelane_b32 v255, s20, 56
	v_writelane_b32 v255, s21, 57
	v_writelane_b32 v255, s22, 58
	v_writelane_b32 v255, s23, 59
	v_writelane_b32 v255, s24, 60
	v_writelane_b32 v255, s25, 61
	v_writelane_b32 v255, s26, 62
	v_writelane_b32 v255, s27, 63
	s_add_u32 s7, s8, 1
	s_load_dwordx2 s[10:11], s[0:1], 0x98
	s_load_dwordx2 s[22:23], s[0:1], 0x50
	s_load_dwordx2 s[12:13], s[0:1], 0x38
	s_load_dwordx2 s[14:15], s[0:1], 0xd8
	v_and_b32_e32 v1, 63, v187
	v_lshrrev_b32_e32 v7, 6, v187
	v_lshrrev_b32_e32 v4, 3, v187
	v_and_b32_e32 v5, 7, v187
	s_nop 1
	v_readfirstlane_b32 s6, v7
	v_mul_u32_u24_e32 v2, 0x41, v7
	v_add_u32_e32 v2, v2, v1
	v_lshlrev_b32_e32 v2, 2, v2
	v_add_u32_e32 v2, 16, v2
	v_lshlrev_b32_e32 v1, 2, v1
	v_mul_u32_u24_e32 v3, 0x208, v5
	v_add_u32_e32 v3, v3, v4
	v_lshlrev_b32_e32 v3, 2, v3
	v_add_u32_e32 v3, 16, v3
	v_lshlrev_b32_e32 v5, 4, v5
	v_lshlrev_b32_e32 v6, 11, v4
	v_add_u32_e32 v6, v6, v5
	s_lshr_b32 s24, s7, 1
	s_lshl_b32 s25, s7, 22
	s_waitcnt lgkmcnt(0)
	s_add_u32 s12, s12, s25
	s_addc_u32 s13, s13, 0
	s_bitcmp1_b32 s7, 0
	s_cselect_b32 s10, s10, s22
	s_cselect_b32 s11, s11, s23
	s_movk_i32 s20, 0x3300
	s_cselect_b32 s20, 0x3000, s20
	s_movk_i32 s21, 0x330
	s_cselect_b32 s21, 0x300, s21
	s_mov_b32 s25, 0xcc0000
	s_cselect_b32 s25, 0xc00000, s25
	s_mul_i32 s25, s25, s24
	s_add_u32 s10, s10, s25
	s_addc_u32 s11, s11, 0
	s_add_u32 s8, s21, 0x100
	s_sub_u32 s4, s2, 16
	s_cmp_lt_u32 s4, s21
	s_cselect_b32 s26, s10, s12
	s_cselect_b32 s27, s11, s13
	s_cselect_b32 s25, s20, 0x1000
	s_cselect_b32 s22, 0, s21
	s_sub_u32 s22, s4, s22
	s_and_b32 s23, s22, 15
	s_lshr_b32 s24, s22, 4
	s_lshl_b32 s23, s23, 6
	s_add_u32 s23, s23, s6
	s_mul_i32 s23, s23, s25
	s_lshl_b32 s24, s24, 8
	s_add_u32 s23, s23, s24
	s_add_u32 s26, s26, s23
	s_addc_u32 s27, s27, 0
	s_lshl_b32 s25, s25, 3
	v_add_u32_e32 v21, s25, v1
	v_add_u32_e32 v22, s25, v21
	v_add_u32_e32 v23, s25, v22
	v_add_u32_e32 v24, s25, v23
	v_add_u32_e32 v25, s25, v24
	v_add_u32_e32 v26, s25, v25
	v_add_u32_e32 v27, s25, v26
	global_load_dword v30, v1, s[26:27]
	global_load_dword v31, v21, s[26:27]
	global_load_dword v32, v22, s[26:27]
	global_load_dword v33, v23, s[26:27]
	global_load_dword v34, v24, s[26:27]
	global_load_dword v35, v25, s[26:27]
	global_load_dword v36, v26, s[26:27]
	global_load_dword v37, v27, s[26:27]
	s_add_u32 s5, s4, 240
	s_cmp_lt_u32 s5, s21
	s_cselect_b32 s26, s10, s12
	s_cselect_b32 s27, s11, s13
	s_cselect_b32 s25, s20, 0x1000
	s_cselect_b32 s22, 0, s21
	s_sub_u32 s22, s5, s22
	s_and_b32 s23, s22, 15
	s_lshr_b32 s24, s22, 4
	s_lshl_b32 s23, s23, 6
	s_add_u32 s23, s23, s6
	s_mul_i32 s23, s23, s25
	s_lshl_b32 s24, s24, 8
	s_add_u32 s23, s23, s24
	s_add_u32 s26, s26, s23
	s_addc_u32 s27, s27, 0
	s_lshl_b32 s25, s25, 3
	v_add_u32_e32 v21, s25, v1
	v_add_u32_e32 v22, s25, v21
	v_add_u32_e32 v23, s25, v22
	v_add_u32_e32 v24, s25, v23
	v_add_u32_e32 v25, s25, v24
	v_add_u32_e32 v26, s25, v25
	v_add_u32_e32 v27, s25, v26
	global_load_dword v40, v1, s[26:27]
	global_load_dword v41, v21, s[26:27]
	global_load_dword v42, v22, s[26:27]
	global_load_dword v43, v23, s[26:27]
	global_load_dword v44, v24, s[26:27]
	global_load_dword v45, v25, s[26:27]
	global_load_dword v46, v26, s[26:27]
	global_load_dword v47, v27, s[26:27]
	s_mov_b32 s7, 0
.Lcvm_j0:
	s_add_u32 s5, s4, 480
	s_cmp_lt_u32 s5, s8
	s_cbranch_scc0 .Lcvm_t0
	s_cmp_lt_u32 s5, s21
	s_cselect_b32 s26, s10, s12
	s_cselect_b32 s27, s11, s13
	s_cselect_b32 s25, s20, 0x1000
	s_cselect_b32 s22, 0, s21
	s_sub_u32 s22, s5, s22
	s_and_b32 s23, s22, 15
	s_lshr_b32 s24, s22, 4
	s_lshl_b32 s23, s23, 6
	s_add_u32 s23, s23, s6
	s_mul_i32 s23, s23, s25
	s_lshl_b32 s24, s24, 8
	s_add_u32 s23, s23, s24
	s_add_u32 s26, s26, s23
	s_addc_u32 s27, s27, 0
	s_lshl_b32 s25, s25, 3
	v_add_u32_e32 v21, s25, v1
	v_add_u32_e32 v22, s25, v21
	v_add_u32_e32 v23, s25, v22
	v_add_u32_e32 v24, s25, v23
	v_add_u32_e32 v25, s25, v24
	v_add_u32_e32 v26, s25, v25
	v_add_u32_e32 v27, s25, v26
	global_load_dword v8, v1, s[26:27]
	global_load_dword v9, v21, s[26:27]
	global_load_dword v10, v22, s[26:27]
	global_load_dword v11, v23, s[26:27]
	global_load_dword v12, v24, s[26:27]
	global_load_dword v13, v25, s[26:27]
	global_load_dword v14, v26, s[26:27]
	global_load_dword v15, v27, s[26:27]
	s_cmp_lt_u32 s7, 2
	s_cbranch_scc1 .Lcvm_w0
	s_waitcnt vmcnt(18)
	s_branch .Lcvm_p0

; __device__ __forceinline__ void conv_matrix(const float* __restrict__ src, int K, int N, int Npad, bf16_t* __restrict__ dst, const float* __restrict__ scale, float* tile) {
;     ...
;   for (int i0 = blockIdx.x; i0 < tot; i0 += 2 * gridDim.x) {
;     const int i1 = i0 + gridDim.x; const bool has1 = i1 < tot;
;     const int k0a = (i0 % nk) * 64, n0a = (i0 / nk) * 64, k0b = has1 ? (i1 % nk) * 64 : 0, n0b = has1 ? (i1 / nk) * 64 : 0;
;     float va[8], vb[8];
; #pragma unroll
;     for (int i = 0; i < 8; ++i) { const int k = k0a + ty + 8 * i, n = n0a + tx; float v = (n < N) ? src[(size_t)k * N + n] : 0.f; if (scale) v *= scale[k]; va[i] = v; }
;     if (has1) {
; #pragma unroll
;       for (int i = 0; i < 8; ++i) { const int k = k0b + ty + 8 * i, n = n0b + tx; float v = (n < N) ? src[(size_t)k * N + n] : 0.f; if (scale) v *= scale[k]; vb[i] = v; }
;     }
.Lcvm_t0:
	s_add_u32 s5, s4, 240
	s_cmp_lt_u32 s5, s8
	s_cbranch_scc0 .Lcvm_z0
	s_waitcnt vmcnt(8)
	s_branch .Lcvm_p0

; __device__ __forceinline__ unsigned cvt_pk_bf16(float lo, float hi) { unsigned r; asm volatile("v_cvt_pk_bf16_f32 %0, %1, %2" : "=v"(r) : "v"(lo), "v"(hi)); return r; }
; __device__ __forceinline__ void conv_matrix(const float* __restrict__ src, int K, int N, int Npad, bf16_t* __restrict__ dst, const float* __restrict__ scale, float* tile) {
;     ...
;     __syncthreads();
; #pragma unroll
;     for (int i = 0; i < 8; ++i) { tile[(ty + 8 * i) * 65 + tx] = va[i]; if (has1) tile[4160 + (ty + 8 * i) * 65 + tx] = vb[i]; }
;     __syncthreads();
;     { float v[8];
; #pragma unroll
;       for (int j = 0; j < 8; ++j) v[j] = tile[(ks + j) * 65 + nl];
;       u32x4 w = {cvt_pk_bf16(v[0], v[1]), cvt_pk_bf16(v[2], v[3]), cvt_pk_bf16(v[4], v[5]), cvt_pk_bf16(v[6], v[7])};
;       *(u32x4*)(dst + (size_t)(n0a + nl) * K + k0a + ks) = w; }
;     if (has1) { float v[8];
; #pragma unroll
;       for (int j = 0; j < 8; ++j) v[j] = tile[4160 + (ks + j) * 65 + nl];
;       u32x4 w = {cvt_pk_bf16(v[0], v[1]), cvt_pk_bf16(v[2], v[3]), cvt_pk_bf16(v[4], v[5]), cvt_pk_bf16(v[6], v[7])};
;       *(u32x4*)(dst + (size_t)(n0b + nl) * K + k0b + ks) = w; }
.Lcvm_p0:
	ds_write_b32 v2, v30 offset:0
	ds_write_b32 v2, v31 offset:2080
	ds_write_b32 v2, v32 offset:4160
	ds_write_b32 v2, v33 offset:6240
	ds_write_b32 v2, v34 offset:8320
	ds_write_b32 v2, v35 offset:10400
	ds_write_b32 v2, v36 offset:12480
	ds_write_b32 v2, v37 offset:14560
	s_cmp_lt_u32 s4, s21
	s_mov_b32 s9, 0x8880000
	s_cselect_b32 s9, 0x8200000, s9
	s_cselect_b32 s22, 0, s21
	s_sub_u32 s22, s4, s22
	s_and_b32 s23, s22, 15
	s_lshr_b32 s24, s22, 4
	s_lshl_b32 s24, s24, 17
	s_lshl_b32 s23, s23, 7
	s_add_u32 s24, s24, s23
	s_add_u32 s24, s24, s9
	s_add_u32 s26, s14, s24
	s_addc_u32 s27, s15, 0
	s_waitcnt lgkmcnt(0)
	s_barrier
	ds_read_b32 v50, v3 offset:0
	ds_read_b32 v51, v3 offset:260
	ds_read_b32 v52, v3 offset:520
	ds_read_b32 v53, v3 offset:780
	ds_read_b32 v54, v3 offset:1040
	ds_read_b32 v55, v3 offset:1300
	ds_read_b32 v56, v3 offset:1560
	ds_read_b32 v57, v3 offset:1820
	s_waitcnt lgkmcnt(0)
	v_cvt_pk_bf16_f32 v60, v50, v51
	v_cvt_pk_bf16_f32 v61, v52, v53
	v_cvt_pk_bf16_f32 v62, v54, v55
	v_cvt_pk_bf16_f32 v63, v56, v57
	global_store_dwordx4 v6, v[60:63], s[26:27]
	s_add_u32 s7, s7, 1
	s_add_u32 s4, s4, 240
	s_cmp_lt_u32 s4, s8
	s_cbranch_scc0 .Lcvm_done
.Lcvm_j1:
	s_add_u32 s5, s4, 480
	s_cmp_lt_u32 s5, s8
	s_cbranch_scc0 .Lcvm_t1
	s_cmp_lt_u32 s5, s21
	s_cselect_b32 s26, s10, s12
	s_cselect_b32 s27, s11, s13
	s_cselect_b32 s25, s20, 0x1000
	s_cselect_b32 s22, 0, s21
	s_sub_u32 s22, s5, s22
	s_and_b32 s23, s22, 15
	s_lshr_b32 s24, s22, 4
	s_lshl_b32 s23, s23, 6
	s_add_u32 s23, s23, s6
	s_mul_i32 s23, s23, s25
	s_lshl_b32 s24, s24, 8
	s_add_u32 s23, s23, s24
	s_add_u32 s26, s26, s23
	s_addc_u32 s27, s27, 0
	s_lshl_b32 s25, s25, 3
	v_add_u32_e32 v21, s25, v1
	v_add_u32_e32 v22, s25, v21
	v_add_u32_e32 v23, s25, v22
	v_add_u32_e32 v24, s25, v23
	v_add_u32_e32 v25, s25, v24
	v_add_u32_e32 v26, s25, v25
	v_add_u32_e32 v27, s25, v26
	global_load_dword v30, v1, s[26:27]
	global_load_dword v31, v21, s[26:27]
	global_load_dword v32, v22, s[26:27]
	global_load_dword v33, v23, s[26:27]
	global_load_dword v34, v24, s[26:27]
	global_load_dword v35, v25, s[26:27]
	global_load_dword v36, v26, s[26:27]
	global_load_dword v37, v27, s[26:27]
	s_cmp_lt_u32 s7, 2
	s_cbranch_scc1 .Lcvm_w1
	s_waitcnt vmcnt(18)
	s_branch .Lcvm_p1

; __device__ __forceinline__ unsigned cvt_pk_bf16(float lo, float hi) { unsigned r; asm volatile("v_cvt_pk_bf16_f32 %0, %1, %2" : "=v"(r) : "v"(lo), "v"(hi)); return r; }
; __device__ __forceinline__ void conv_matrix(const float* __restrict__ src, int K, int N, int Npad, bf16_t* __restrict__ dst, const float* __restrict__ scale, float* tile) {
;     ...
;     __syncthreads();
; #pragma unroll
;     for (int i = 0; i < 8; ++i) { tile[(ty + 8 * i) * 65 + tx] = va[i]; if (has1) tile[4160 + (ty + 8 * i) * 65 + tx] = vb[i]; }
;     __syncthreads();
;     { float v[8];
; #pragma unroll
;       for (int j = 0; j < 8; ++j) v[j] = tile[(ks + j) * 65 + nl];
;       u32x4 w = {cvt_pk_bf16(v[0], v[1]), cvt_pk_bf16(v[2], v[3]), cvt_pk_bf16(v[4], v[5]), cvt_pk_bf16(v[6], v[7])};
;       *(u32x4*)(dst + (size_t)(n0a + nl) * K + k0a + ks) = w; }
;     if (has1) { float v[8];
; #pragma unroll
;       for (int j = 0; j < 8; ++j) v[j] = tile[4160 + (ks + j) * 65 + nl];
;       u32x4 w = {cvt_pk_bf16(v[0], v[1]), cvt_pk_bf16(v[2], v[3]), cvt_pk_bf16(v[4], v[5]), cvt_pk_bf16(v[6], v[7])};
;       *(u32x4*)(dst + (size_t)(n0b + nl) * K + k0b + ks) = w; }
.Lcvm_p1:
	ds_write_b32 v2, v40 offset:16640
	ds_write_b32 v2, v41 offset:18720
	ds_write_b32 v2, v42 offset:20800
	ds_write_b32 v2, v43 offset:22880
	ds_write_b32 v2, v44 offset:24960
	ds_write_b32 v2, v45 offset:27040
	ds_write_b32 v2, v46 offset:29120
	ds_write_b32 v2, v47 offset:31200
	s_cmp_lt_u32 s4, s21
	s_mov_b32 s9, 0x8880000
	s_cselect_b32 s9, 0x8200000, s9
	s_cselect_b32 s22, 0, s21
	s_sub_u32 s22, s4, s22
	s_and_b32 s23, s22, 15
	s_lshr_b32 s24, s22, 4
	s_lshl_b32 s24, s24, 17
	s_lshl_b32 s23, s23, 7
	s_add_u32 s24, s24, s23
	s_add_u32 s24, s24, s9
	s_add_u32 s26, s14, s24
	s_addc_u32 s27, s15, 0
	s_waitcnt lgkmcnt(0)
	s_barrier
	ds_read_b32 v50, v3 offset:16640
	ds_read_b32 v51, v3 offset:16900
	ds_read_b32 v52, v3 offset:17160
	ds_read_b32 v53, v3 offset:17420
	ds_read_b32 v54, v3 offset:17680
	ds_read_b32 v55, v3 offset:17940
	ds_read_b32 v56, v3 offset:18200
	ds_read_b32 v57, v3 offset:18460
	s_waitcnt lgkmcnt(0)
	v_cvt_pk_bf16_f32 v60, v50, v51
	v_cvt_pk_bf16_f32 v61, v52, v53
	v_cvt_pk_bf16_f32 v62, v54, v55
	v_cvt_pk_bf16_f32 v63, v56, v57
	global_store_dwordx4 v6, v[60:63], s[26:27]
	s_add_u32 s7, s7, 1
	s_add_u32 s4, s4, 240
	s_cmp_lt_u32 s4, s8
	s_cbranch_scc0 .Lcvm_done
.Lcvm_j2:
	s_add_u32 s5, s4, 480
	s_cmp_lt_u32 s5, s8
	s_cbranch_scc0 .Lcvm_t2
	s_cmp_lt_u32 s5, s21
	s_cselect_b32 s26, s10, s12
	s_cselect_b32 s27, s11, s13
	s_cselect_b32 s25, s20, 0x1000
	s_cselect_b32 s22, 0, s21
	s_sub_u32 s22, s5, s22
	s_and_b32 s23, s22, 15
	s_lshr_b32 s24, s22, 4
	s_lshl_b32 s23, s23, 6
	s_add_u32 s23, s23, s6
	s_mul_i32 s23, s23, s25
	s_lshl_b32 s24, s24, 8
	s_add_u32 s23, s23, s24
	s_add_u32 s26, s26, s23
	s_addc_u32 s27, s27, 0
	s_lshl_b32 s25, s25, 3
	v_add_u32_e32 v21, s25, v1
	v_add_u32_e32 v22, s25, v21
	v_add_u32_e32 v23, s25, v22
	v_add_u32_e32 v24, s25, v23
	v_add_u32_e32 v25, s25, v24
	v_add_u32_e32 v26, s25, v25
	v_add_u32_e32 v27, s25, v26
	global_load_dword v40, v1, s[26:27]
	global_load_dword v41, v21, s[26:27]
	global_load_dword v42, v22, s[26:27]
	global_load_dword v43, v23, s[26:27]
	global_load_dword v44, v24, s[26:27]
	global_load_dword v45, v25, s[26:27]
	global_load_dword v46, v26, s[26:27]
	global_load_dword v47, v27, s[26:27]
	s_cmp_lt_u32 s7, 2
	s_cbranch_scc1 .Lcvm_w2
	s_waitcnt vmcnt(18)
	s_branch .Lcvm_p2

; __device__ __forceinline__ unsigned cvt_pk_bf16(float lo, float hi) { unsigned r; asm volatile("v_cvt_pk_bf16_f32 %0, %1, %2" : "=v"(r) : "v"(lo), "v"(hi)); return r; }
; __device__ __forceinline__ void conv_matrix(const float* __restrict__ src, int K, int N, int Npad, bf16_t* __restrict__ dst, const float* __restrict__ scale, float* tile) {
;     ...
;     __syncthreads();
; #pragma unroll
;     for (int i = 0; i < 8; ++i) { tile[(ty + 8 * i) * 65 + tx] = va[i]; if (has1) tile[4160 + (ty + 8 * i) * 65 + tx] = vb[i]; }
;     __syncthreads();
;     { float v[8];
; #pragma unroll
;       for (int j = 0; j < 8; ++j) v[j] = tile[(ks + j) * 65 + nl];
;       u32x4 w = {cvt_pk_bf16(v[0], v[1]), cvt_pk_bf16(v[2], v[3]), cvt_pk_bf16(v[4], v[5]), cvt_pk_bf16(v[6], v[7])};
;       *(u32x4*)(dst + (size_t)(n0a + nl) * K + k0a + ks) = w; }
;     if (has1) { float v[8];
; #pragma unroll
;       for (int j = 0; j < 8; ++j) v[j] = tile[4160 + (ks + j) * 65 + nl];
;       u32x4 w = {cvt_pk_bf16(v[0], v[1]), cvt_pk_bf16(v[2], v[3]), cvt_pk_bf16(v[4], v[5]), cvt_pk_bf16(v[6], v[7])};
;       *(u32x4*)(dst + (size_t)(n0b + nl) * K + k0b + ks) = w; }
.Lcvm_p2:
	ds_write_b32 v2, v8 offset:33280
	ds_write_b32 v2, v9 offset:35360
	ds_write_b32 v2, v10 offset:37440
	ds_write_b32 v2, v11 offset:39520
	ds_write_b32 v2, v12 offset:41600
	ds_write_b32 v2, v13 offset:43680
	ds_write_b32 v2, v14 offset:45760
	ds_write_b32 v2, v15 offset:47840
	s_cmp_lt_u32 s4, s21
	s_mov_b32 s9, 0x8880000
	s_cselect_b32 s9, 0x8200000, s9
	s_cselect_b32 s22, 0, s21
	s_sub_u32 s22, s4, s22
	s_and_b32 s23, s22, 15
	s_lshr_b32 s24, s22, 4
	s_lshl_b32 s24, s24, 17
	s_lshl_b32 s23, s23, 7
	s_add_u32 s24, s24, s23
	s_add_u32 s24, s24, s9
	s_add_u32 s26, s14, s24
	s_addc_u32 s27, s15, 0
	s_waitcnt lgkmcnt(0)
	s_barrier
	ds_read_b32 v50, v3 offset:33280
	ds_read_b32 v51, v3 offset:33540
	ds_read_b32 v52, v3 offset:33800
	ds_read_b32 v53, v3 offset:34060
	ds_read_b32 v54, v3 offset:34320
	ds_read_b32 v55, v3 offset:34580
	ds_read_b32 v56, v3 offset:34840
	ds_read_b32 v57, v3 offset:35100
	s_waitcnt lgkmcnt(0)
	v_cvt_pk_bf16_f32 v60, v50, v51
	v_cvt_pk_bf16_f32 v61, v52, v53
	v_cvt_pk_bf16_f32 v62, v54, v55
	v_cvt_pk_bf16_f32 v63, v56, v57
	global_store_dwordx4 v6, v[60:63], s[26:27]
	s_add_u32 s7, s7, 1
	s_add_u32 s4, s4, 240
	s_cmp_lt_u32 s4, s8
	s_cbranch_scc0 .Lcvm_done
	s_branch .Lcvm_j0
.Lcvm_done:
	s_nop 1
	v_readlane_b32 s4, v255, 46
	v_readlane_b32 s5, v255, 47
	v_readlane_b32 s6, v255, 48
	v_readlane_b32 s7, v255, 49
	v_readlane_b32 s10, v255, 50
	v_readlane_b32 s11, v255, 51
	v_readlane_b32 s12, v255, 52
	v_readlane_b32 s13, v255, 53
	v_readlane_b32 s14, v255, 54
	v_readlane_b32 s15, v255, 55
	v_readlane_b32 s20, v255, 56
	v_readlane_b32 s21, v255, 57
	v_readlane_b32 s22, v255, 58
	v_readlane_b32 s23, v255, 59
	v_readlane_b32 s24, v255, 60
	v_readlane_b32 s25, v255, 61
	v_readlane_b32 s26, v255, 62
	v_readlane_b32 s27, v255, 63
